# EpiGlu epilogue: all 16 z loads issued up front (address slices re-run in a renamed dry pass), counted vmcnt waits
# speedup vs baseline: 1.0074x; 1.0074x over previous
.LBB0_235:
	v_lshrrev_b32_e32 v26, 3, v108
	v_and_b32_e32 v27, 4, v26
	v_and_or_b32 v28, v107, 64, s1
	v_or_b32_e32 v29, s0, v106
	v_add_u32_e32 v26, v29, v109
	v_lshrrev_b32_e32 v30, 4, v28
	s_movk_i32 s3, 0x4200
	v_mul_lo_u32 v29, v30, s3
	v_ashrrev_i32_e32 v30, 31, v26
	v_ashrrev_i32_e32 v31, 31, v29
	v_mov_b32_e32 v32, v29
	v_mov_b32_e32 v33, v31
	v_mov_b32_e32 v34, v26
	v_mov_b32_e32 v35, v30
	v_lshl_add_u64 v[36:37], v[32:33], 0, v[34:35]
	v_readlane_b32 s6, v254, 3
	v_lshlrev_b64 v[32:33], 5, v[36:37]
	v_readlane_b32 s7, v254, 4
	v_lshlrev_b32_e32 v34, 1, v27
	v_or_b32_e32 v35, v27, v28
	v_lshl_add_u64 v[36:37], s[6:7], 0, v[32:33]
	v_mov_b32_e32 v32, v34
	v_mov_b32_e32 v33, v193
	v_lshl_add_u64 v[38:39], v[36:37], 0, v[32:33]
	global_load_dwordx2 v[32:33], v[38:39], off
	v_bitop3_b32 v40, v35, 12, 8 bitop3:0xc8
	v_lshlrev_b32_e32 v27, 1, v40
	v_mov_b32_e32 v38, v193
	v_mov_b32_e32 v42, v27
	v_mov_b32_e32 v43, v38
	v_lshl_add_u64 v[44:45], v[36:37], 0, v[42:43]
	global_load_dwordx2 v[42:43], v[44:45], off
	v_or_b32_e32 v39, 16, v28
	v_lshrrev_b32_e32 v36, 4, v39
	v_mul_lo_u32 v39, v36, s3
	v_ashrrev_i32_e32 v41, 31, v39
	v_mov_b32_e32 v46, v39
	v_mov_b32_e32 v47, v41
	v_mov_b32_e32 v48, v26
	v_mov_b32_e32 v49, v30
	v_lshl_add_u64 v[110:111], v[46:47], 0, v[48:49]
	v_lshlrev_b64 v[36:37], 5, v[110:111]
	v_lshl_add_u64 v[46:47], s[6:7], 0, v[36:37]
	v_mov_b32_e32 v36, v34
	v_mov_b32_e32 v37, v193
	v_lshl_add_u64 v[48:49], v[46:47], 0, v[36:37]
	global_load_dwordx2 v[36:37], v[48:49], off
	global_load_dwordx2 v[46:47], v[48:49], off offset:16
	v_or_b32_e32 v110, 32, v26
	v_ashrrev_i32_e32 v48, 31, v110
	v_mov_b32_e32 v116, v29
	v_mov_b32_e32 v117, v31
	v_mov_b32_e32 v118, v110
	v_mov_b32_e32 v119, v48
	v_lshl_add_u64 v[120:121], v[116:117], 0, v[118:119]
	v_lshlrev_b64 v[116:117], 5, v[120:121]
	v_lshl_add_u64 v[118:119], s[6:7], 0, v[116:117]
	v_mov_b32_e32 v44, v34
	v_mov_b32_e32 v45, v193
	v_lshl_add_u64 v[120:121], v[118:119], 0, v[44:45]
	global_load_dwordx2 v[44:45], v[120:121], off
	v_mov_b32_e32 v122, v27
	v_mov_b32_e32 v123, v38
	v_lshl_add_u64 v[124:125], v[118:119], 0, v[122:123]
	global_load_dwordx2 v[118:119], v[124:125], off
	v_mov_b32_e32 v122, v39
	v_mov_b32_e32 v123, v41
	v_mov_b32_e32 v136, v110
	v_mov_b32_e32 v137, v48
	v_lshl_add_u64 v[138:139], v[122:123], 0, v[136:137]
	v_lshlrev_b64 v[122:123], 5, v[138:139]
	v_lshl_add_u64 v[136:137], s[6:7], 0, v[122:123]
	v_mov_b32_e32 v122, v34
	v_mov_b32_e32 v123, v193
	v_lshl_add_u64 v[138:139], v[136:137], 0, v[122:123]
	global_load_dwordx2 v[122:123], v[138:139], off
	global_load_dwordx2 v[136:137], v[138:139], off offset:16
	v_or_b32_e32 v27, 32, v28
	v_lshrrev_b32_e32 v29, 4, v27
	v_mul_lo_u32 v27, v29, s3
	v_ashrrev_i32_e32 v31, 31, v27
	v_mov_b32_e32 v38, v27
	v_mov_b32_e32 v39, v31
	v_mov_b32_e32 v40, v26
	v_mov_b32_e32 v41, v30
	v_lshl_add_u64 v[140:141], v[38:39], 0, v[40:41]
	v_lshlrev_b64 v[38:39], 5, v[140:141]
	v_lshl_add_u64 v[40:41], s[6:7], 0, v[38:39]
	v_mov_b32_e32 v38, v34
	v_mov_b32_e32 v39, v193
	v_lshl_add_u64 v[138:139], v[40:41], 0, v[38:39]
	global_load_dwordx2 v[38:39], v[138:139], off
	v_or_b32_e32 v49, 40, v35
	v_lshrrev_b32_e32 v29, 4, v49
	v_mul_lo_u32 v49, v29, s3
	v_ashrrev_i32_e32 v40, 31, v49
	v_mov_b32_e32 v124, v49
	v_mov_b32_e32 v125, v40
	v_mov_b32_e32 v140, v26
	v_mov_b32_e32 v141, v30
	v_lshl_add_u64 v[142:143], v[124:125], 0, v[140:141]
	v_lshlrev_b64 v[124:125], 5, v[142:143]
	v_bitop3_b32 v41, v35, 12, 40 bitop3:0xc8
	v_lshl_add_u64 v[140:141], s[6:7], 0, v[124:125]
	v_lshlrev_b32_e32 v35, 1, v41
	v_mov_b32_e32 v41, v193
	v_mov_b32_e32 v124, v35
	v_mov_b32_e32 v125, v41
	v_lshl_add_u64 v[142:143], v[140:141], 0, v[124:125]
	global_load_dwordx2 v[124:125], v[142:143], off
	v_or_b32_e32 v29, 48, v28
	v_lshrrev_b32_e32 v111, 4, v29
	v_mul_lo_u32 v29, v111, s3
	v_ashrrev_i32_e32 v111, 31, v29
	v_mov_b32_e32 v140, v29
	v_mov_b32_e32 v141, v111
	v_mov_b32_e32 v144, v26
	v_mov_b32_e32 v145, v30
	v_lshl_add_u64 v[146:147], v[140:141], 0, v[144:145]
	v_lshlrev_b64 v[140:141], 5, v[146:147]
	v_lshl_add_u64 v[144:145], s[6:7], 0, v[140:141]
	v_mov_b32_e32 v140, v34
	v_mov_b32_e32 v141, v193
	v_lshl_add_u64 v[146:147], v[144:145], 0, v[140:141]
	global_load_dwordx2 v[140:141], v[146:147], off
	global_load_dwordx2 v[144:145], v[146:147], off offset:16
	v_mov_b32_e32 v148, v27
	v_mov_b32_e32 v149, v31
	v_mov_b32_e32 v150, v110
	v_mov_b32_e32 v151, v48
	v_lshl_add_u64 v[152:153], v[148:149], 0, v[150:151]
	v_lshlrev_b64 v[148:149], 5, v[152:153]
	v_lshl_add_u64 v[150:151], s[6:7], 0, v[148:149]
	v_mov_b32_e32 v148, v34
	v_mov_b32_e32 v149, v193
	v_lshl_add_u64 v[152:153], v[150:151], 0, v[148:149]
	global_load_dwordx2 v[26:27], v[152:153], off
	v_mov_b32_e32 v30, v49
	v_mov_b32_e32 v31, v40
	v_mov_b32_e32 v148, v110
	v_mov_b32_e32 v149, v48
	v_lshl_add_u64 v[154:155], v[30:31], 0, v[148:149]
	v_lshlrev_b64 v[30:31], 5, v[154:155]
	v_lshl_add_u64 v[148:149], s[6:7], 0, v[30:31]
	v_mov_b32_e32 v30, v35
	v_mov_b32_e32 v31, v41
	v_lshl_add_u64 v[150:151], v[148:149], 0, v[30:31]
	global_load_dwordx2 v[30:31], v[150:151], off
	v_mov_b32_e32 v154, v29
	v_mov_b32_e32 v155, v111
	v_mov_b32_e32 v156, v110
	v_mov_b32_e32 v157, v48
	v_lshl_add_u64 v[158:159], v[154:155], 0, v[156:157]
	v_lshlrev_b64 v[148:149], 5, v[158:159]
	v_lshl_add_u64 v[154:155], s[6:7], 0, v[148:149]
	v_mov_b32_e32 v148, v34
	v_mov_b32_e32 v149, v193
	v_lshl_add_u64 v[156:157], v[154:155], 0, v[148:149]
	global_load_dwordx2 v[148:149], v[156:157], off
	global_load_dwordx2 v[154:155], v[156:157], off offset:16
	v_lshrrev_b32_e32 v0, 3, v108
	v_and_b32_e32 v9, 4, v0
	v_and_or_b32 v22, v107, 64, s1
	v_or_b32_e32 v0, s0, v106
	v_add_u32_e32 v6, v0, v109
	v_lshrrev_b32_e32 v0, 4, v22
	s_movk_i32 s3, 0x4200
	v_mul_lo_u32 v0, v0, s3
	v_ashrrev_i32_e32 v7, 31, v6
	v_ashrrev_i32_e32 v1, 31, v0
	v_lshl_add_u64 v[4:5], v[0:1], 0, v[6:7]
	v_readlane_b32 s6, v254, 3
	v_lshlrev_b64 v[4:5], 5, v[4:5]
	v_readlane_b32 s7, v254, 4
	v_lshlrev_b32_e32 v192, 1, v9
	v_or_b32_e32 v8, v9, v22
	v_lshl_add_u64 v[4:5], s[6:7], 0, v[4:5]
	v_lshl_add_u64 v[10:11], v[4:5], 0, v[192:193]
	v_accvgpr_read_b32 v134, a32
	v_ashrrev_i32_e32 v9, 31, v8
	v_accvgpr_read_b32 v133, a33
	v_lshlrev_b64 v[14:15], 1, v[8:9]
	v_mul_f32_e32 v9, 0xbfb8aa3b, v134
	v_accvgpr_read_b32 v132, a34
	v_exp_f32_e32 v12, v9
	v_mul_f32_e32 v9, 0xbfb8aa3b, v133
	v_exp_f32_e32 v16, v9
	v_mul_f32_e32 v9, 0xbfb8aa3b, v132
	v_exp_f32_e32 v13, v9
	v_accvgpr_read_b32 v131, a35
	v_mul_f32_e32 v9, 0xbfb8aa3b, v131
	v_exp_f32_e32 v17, v9
	v_readlane_b32 s4, v253, 61
	v_lshlrev_b64 v[2:3], 11, v[6:7]
	v_readlane_b32 s5, v253, 62
	v_accvgpr_read_b32 v130, a36
	v_accvgpr_read_b32 v128, a38
	v_lshl_add_u64 v[2:3], s[4:5], 0, v[2:3]
	v_lshl_add_u64 v[2:3], v[2:3], 0, v[14:15]
	v_accvgpr_read_b32 v129, a37
	v_accvgpr_read_b32 v127, a39
	v_accvgpr_read_b32 v105, a40
	v_accvgpr_read_b32 v104, a41
	v_accvgpr_read_b32 v103, a42
	v_accvgpr_read_b32 v102, a43
	v_accvgpr_read_b32 v101, a44
	v_accvgpr_read_b32 v100, a45
	v_accvgpr_read_b32 v99, a46
	v_accvgpr_read_b32 v98, a47
	v_accvgpr_read_b32 v97, a48
	v_accvgpr_read_b32 v96, a49
	v_accvgpr_read_b32 v95, a50
	v_accvgpr_read_b32 v94, a51
	v_accvgpr_read_b32 v93, a52
	v_accvgpr_read_b32 v92, a53
	v_accvgpr_read_b32 v91, a54
	v_accvgpr_read_b32 v90, a55
	v_accvgpr_read_b32 v89, a56
	v_accvgpr_read_b32 v88, a57
	v_accvgpr_read_b32 v87, a58
	v_accvgpr_read_b32 v86, a59
	v_accvgpr_read_b32 v85, a60
	v_accvgpr_read_b32 v84, a61
	v_accvgpr_read_b32 v83, a62
	v_accvgpr_read_b32 v82, a63
	v_accvgpr_read_b32 v81, a0
	v_accvgpr_read_b32 v80, a1
	v_accvgpr_read_b32 v79, a2
	v_accvgpr_read_b32 v78, a3
	v_accvgpr_read_b32 v77, a4
	v_accvgpr_read_b32 v75, a6
	v_accvgpr_read_b32 v76, a5
	v_accvgpr_read_b32 v74, a7
	v_accvgpr_read_b32 v73, a8
	v_accvgpr_read_b32 v71, a10
	v_accvgpr_read_b32 v72, a9
	v_accvgpr_read_b32 v70, a11
	v_accvgpr_read_b32 v68, a13
	v_accvgpr_read_b32 v69, a12
	v_accvgpr_read_b32 v67, a14
	v_accvgpr_read_b32 v66, a15
	v_accvgpr_read_b32 v65, a16
	v_accvgpr_read_b32 v63, a18
	v_accvgpr_read_b32 v64, a17
	v_accvgpr_read_b32 v62, a19
	v_accvgpr_read_b32 v61, a20
	v_accvgpr_read_b32 v59, a22
	v_accvgpr_read_b32 v60, a21
	v_accvgpr_read_b32 v58, a23
	v_accvgpr_read_b32 v57, a24
	v_accvgpr_read_b32 v55, a26
	v_accvgpr_read_b32 v56, a25
	v_accvgpr_read_b32 v54, a27
	v_accvgpr_read_b32 v52, a29
	v_accvgpr_read_b32 v53, a28
	v_accvgpr_read_b32 v51, a30
	v_accvgpr_read_b32 v50, a31
	s_waitcnt vmcnt(15)
	v_mov_b32_e32 v10, v32
	v_mov_b32_e32 v11, v33
	v_lshlrev_b32_e32 v9, 16, v11
	v_lshlrev_b32_e32 v18, 16, v10
	v_and_b32_e32 v19, 0xffff0000, v11
	v_and_b32_e32 v20, 0xffff0000, v10
	v_pk_add_f32 v[10:11], v[12:13], 1.0 op_sel_hi:[1,0]
	s_nop 0
	v_rcp_f32_e32 v13, v10
	s_nop 0
	v_mul_f32_e32 v12, v18, v13
	v_rcp_f32_e32 v13, v11
	s_nop 0
	v_mul_f32_e32 v9, v9, v13
	v_pk_add_f32 v[10:11], v[16:17], 1.0 op_sel_hi:[1,0]
	s_nop 0
	v_rcp_f32_e32 v16, v10
	s_nop 0
	v_mul_f32_e32 v10, v20, v16
	v_rcp_f32_e32 v16, v11
	s_nop 0
	v_mul_f32_e32 v11, v19, v16
	v_cvt_pk_bf16_f32 v11, v9, v11
	v_cvt_pk_bf16_f32 v10, v12, v10
	v_bitop3_b32 v9, v8, 12, 8 bitop3:0xc8
	global_store_dwordx2 v[2:3], v[10:11], off
	v_lshlrev_b32_e32 v10, 1, v9
	v_mov_b32_e32 v11, v193
	v_lshl_add_u64 v[16:17], v[4:5], 0, v[10:11]
	v_mul_f32_e32 v4, 0xbfb8aa3b, v130
	v_mul_f32_e32 v5, 0xbfb8aa3b, v128
	v_exp_f32_e32 v12, v4
	v_exp_f32_e32 v13, v5
	v_mul_f32_e32 v4, 0xbfb8aa3b, v129
	v_mul_f32_e32 v5, 0xbfb8aa3b, v127
	v_exp_f32_e32 v4, v4
	v_pk_add_f32 v[12:13], v[12:13], 1.0 op_sel_hi:[1,0]
	v_exp_f32_e32 v5, v5
	s_waitcnt vmcnt(15)
	v_mov_b32_e32 v16, v42
	v_mov_b32_e32 v17, v43
	v_lshlrev_b32_e32 v18, 16, v16
	v_rcp_f32_e32 v20, v12
	v_lshlrev_b32_e32 v9, 16, v17
	v_and_b32_e32 v16, 0xffff0000, v16
	v_pk_add_f32 v[4:5], v[4:5], 1.0 op_sel_hi:[1,0]
	v_mul_f32_e32 v12, v18, v20
	v_rcp_f32_e32 v19, v13
	v_and_b32_e32 v17, 0xffff0000, v17
	v_mul_f32_e32 v9, v9, v19
	v_rcp_f32_e32 v18, v4
	s_nop 0
	v_mul_f32_e32 v4, v16, v18
	v_rcp_f32_e32 v16, v5
	s_nop 0
	v_mul_f32_e32 v5, v17, v16
	v_cvt_pk_bf16_f32 v5, v9, v5
	v_cvt_pk_bf16_f32 v4, v12, v4
	global_store_dwordx2 v[2:3], v[4:5], off offset:16
	v_or_b32_e32 v4, 16, v22
	v_lshrrev_b32_e32 v4, 4, v4
	v_mul_lo_u32 v12, v4, s3
	v_ashrrev_i32_e32 v13, 31, v12
	v_lshl_add_u64 v[4:5], v[12:13], 0, v[6:7]
	v_lshlrev_b64 v[4:5], 5, v[4:5]
	v_lshl_add_u64 v[4:5], s[6:7], 0, v[4:5]
	v_lshl_add_u64 v[4:5], v[4:5], 0, v[192:193]
	v_mul_f32_e32 v9, 0xbfb8aa3b, v105
	v_exp_f32_e32 v18, v9
	v_mul_f32_e32 v9, 0xbfb8aa3b, v104
	v_exp_f32_e32 v16, v9
	v_mul_f32_e32 v9, 0xbfb8aa3b, v103
	v_exp_f32_e32 v19, v9
	v_mul_f32_e32 v9, 0xbfb8aa3b, v102
	v_exp_f32_e32 v17, v9
	v_pk_add_f32 v[18:19], v[18:19], 1.0 op_sel_hi:[1,0]
	v_pk_add_f32 v[16:17], v[16:17], 1.0 op_sel_hi:[1,0]
	s_waitcnt vmcnt(15)
	v_mov_b32_e32 v20, v36
	v_mov_b32_e32 v21, v37
	v_lshlrev_b32_e32 v23, 16, v20
	v_rcp_f32_e32 v25, v18
	v_lshlrev_b32_e32 v9, 16, v21
	v_and_b32_e32 v20, 0xffff0000, v20
	v_and_b32_e32 v21, 0xffff0000, v21
	v_mul_f32_e32 v18, v23, v25
	v_rcp_f32_e32 v24, v19
	s_nop 0
	v_mul_f32_e32 v9, v9, v24
	v_rcp_f32_e32 v23, v16
	s_nop 0
	v_mul_f32_e32 v16, v20, v23
	v_rcp_f32_e32 v20, v17
	s_nop 0
	v_mul_f32_e32 v17, v21, v20
	v_cvt_pk_bf16_f32 v17, v9, v17
	v_cvt_pk_bf16_f32 v16, v18, v16
	global_store_dwordx2 v[2:3], v[16:17], off offset:32
	v_mul_f32_e32 v9, 0xbfb8aa3b, v101
	v_exp_f32_e32 v16, v9
	v_mul_f32_e32 v9, 0xbfb8aa3b, v100
	v_exp_f32_e32 v18, v9
	v_mul_f32_e32 v9, 0xbfb8aa3b, v99
	v_exp_f32_e32 v17, v9
	v_mul_f32_e32 v9, 0xbfb8aa3b, v98
	v_exp_f32_e32 v19, v9
	s_waitcnt vmcnt(15)
	v_mov_b32_e32 v4, v46
	v_mov_b32_e32 v5, v47
	v_lshlrev_b32_e32 v9, 16, v5
	v_lshlrev_b32_e32 v20, 16, v4
	v_and_b32_e32 v21, 0xffff0000, v5
	v_and_b32_e32 v23, 0xffff0000, v4
	v_pk_add_f32 v[4:5], v[16:17], 1.0 op_sel_hi:[1,0]
	s_nop 0
	v_rcp_f32_e32 v17, v4
	s_nop 0
	v_mul_f32_e32 v16, v20, v17
	v_rcp_f32_e32 v17, v5
	s_nop 0
	v_mul_f32_e32 v9, v9, v17
	v_pk_add_f32 v[4:5], v[18:19], 1.0 op_sel_hi:[1,0]
	s_nop 0
	v_rcp_f32_e32 v18, v4
	s_nop 0
	v_mul_f32_e32 v4, v23, v18
	v_rcp_f32_e32 v18, v5
	s_nop 0
	v_mul_f32_e32 v5, v21, v18
	v_cvt_pk_bf16_f32 v5, v9, v5
	v_cvt_pk_bf16_f32 v4, v16, v4
	global_store_dwordx2 v[2:3], v[4:5], off offset:48
	v_or_b32_e32 v4, 32, v6
	v_ashrrev_i32_e32 v5, 31, v4
	v_lshl_add_u64 v[0:1], v[0:1], 0, v[4:5]
	v_lshlrev_b64 v[0:1], 5, v[0:1]
	v_lshl_add_u64 v[16:17], s[6:7], 0, v[0:1]
	v_lshl_add_u64 v[20:21], v[16:17], 0, v[192:193]
	v_lshlrev_b64 v[18:19], 11, v[4:5]
	v_mul_f32_e32 v9, 0xbfb8aa3b, v97
	v_lshl_add_u64 v[0:1], s[4:5], 0, v[18:19]
	v_exp_f32_e32 v18, v9
	v_mul_f32_e32 v9, 0xbfb8aa3b, v96
	v_lshl_add_u64 v[0:1], v[0:1], 0, v[14:15]
	v_exp_f32_e32 v14, v9
	v_mul_f32_e32 v9, 0xbfb8aa3b, v95
	v_exp_f32_e32 v19, v9
	v_mul_f32_e32 v9, 0xbfb8aa3b, v94
	v_exp_f32_e32 v15, v9
	v_lshl_add_u64 v[16:17], v[16:17], 0, v[10:11]
	v_pk_add_f32 v[18:19], v[18:19], 1.0 op_sel_hi:[1,0]
	v_pk_add_f32 v[14:15], v[14:15], 1.0 op_sel_hi:[1,0]
	s_waitcnt vmcnt(15)
	v_mov_b32_e32 v20, v44
	v_mov_b32_e32 v21, v45
	v_lshlrev_b32_e32 v23, 16, v20
	v_rcp_f32_e32 v25, v18
	v_lshlrev_b32_e32 v9, 16, v21
	v_and_b32_e32 v20, 0xffff0000, v20
	v_and_b32_e32 v21, 0xffff0000, v21
	v_mul_f32_e32 v18, v23, v25
	v_rcp_f32_e32 v24, v19
	s_nop 0
	v_mul_f32_e32 v9, v9, v24
	v_rcp_f32_e32 v23, v14
	s_nop 0
	v_mul_f32_e32 v14, v20, v23
	v_rcp_f32_e32 v20, v15
	s_nop 0
	v_mul_f32_e32 v15, v21, v20
	v_cvt_pk_bf16_f32 v15, v9, v15
	v_cvt_pk_bf16_f32 v14, v18, v14
	global_store_dwordx2 v[0:1], v[14:15], off
	v_mul_f32_e32 v9, 0xbfb8aa3b, v93
	v_exp_f32_e32 v14, v9
	v_mul_f32_e32 v9, 0xbfb8aa3b, v92
	v_exp_f32_e32 v10, v9
	v_mul_f32_e32 v9, 0xbfb8aa3b, v91
	v_exp_f32_e32 v15, v9
	v_mul_f32_e32 v9, 0xbfb8aa3b, v90
	v_exp_f32_e32 v11, v9
	v_pk_add_f32 v[14:15], v[14:15], 1.0 op_sel_hi:[1,0]
	v_pk_add_f32 v[10:11], v[10:11], 1.0 op_sel_hi:[1,0]
	s_waitcnt vmcnt(15)
	v_mov_b32_e32 v16, v118
	v_mov_b32_e32 v17, v119
	v_lshlrev_b32_e32 v18, 16, v16
	v_rcp_f32_e32 v20, v14
	v_lshlrev_b32_e32 v9, 16, v17
	v_and_b32_e32 v16, 0xffff0000, v16
	v_and_b32_e32 v17, 0xffff0000, v17
	v_mul_f32_e32 v14, v18, v20
	v_rcp_f32_e32 v19, v15
	s_nop 0
	v_mul_f32_e32 v9, v9, v19
	v_rcp_f32_e32 v18, v10
	s_nop 0
	v_mul_f32_e32 v10, v16, v18
	v_rcp_f32_e32 v16, v11
	s_nop 0
	v_mul_f32_e32 v11, v17, v16
	v_cvt_pk_bf16_f32 v11, v9, v11
	v_cvt_pk_bf16_f32 v10, v14, v10
	global_store_dwordx2 v[0:1], v[10:11], off offset:16
	v_lshl_add_u64 v[10:11], v[12:13], 0, v[4:5]
	v_lshlrev_b64 v[10:11], 5, v[10:11]
	v_lshl_add_u64 v[10:11], s[6:7], 0, v[10:11]
	v_lshl_add_u64 v[10:11], v[10:11], 0, v[192:193]
	v_mul_f32_e32 v9, 0xbfb8aa3b, v89
	v_exp_f32_e32 v14, v9
	v_mul_f32_e32 v9, 0xbfb8aa3b, v88
	v_exp_f32_e32 v12, v9
	v_mul_f32_e32 v9, 0xbfb8aa3b, v87
	v_exp_f32_e32 v15, v9
	v_mul_f32_e32 v9, 0xbfb8aa3b, v86
	v_exp_f32_e32 v13, v9
	v_pk_add_f32 v[14:15], v[14:15], 1.0 op_sel_hi:[1,0]
	v_pk_add_f32 v[12:13], v[12:13], 1.0 op_sel_hi:[1,0]
	s_waitcnt vmcnt(15)
	v_mov_b32_e32 v16, v122
	v_mov_b32_e32 v17, v123
	v_lshlrev_b32_e32 v18, 16, v16
	v_rcp_f32_e32 v20, v14
	v_lshlrev_b32_e32 v9, 16, v17
	v_and_b32_e32 v16, 0xffff0000, v16
	v_and_b32_e32 v17, 0xffff0000, v17
	v_mul_f32_e32 v14, v18, v20
	v_rcp_f32_e32 v19, v15
	s_nop 0
	v_mul_f32_e32 v9, v9, v19
	v_rcp_f32_e32 v18, v12
	s_nop 0
	v_mul_f32_e32 v12, v16, v18
	v_rcp_f32_e32 v16, v13
	s_nop 0
	v_mul_f32_e32 v13, v17, v16
	v_cvt_pk_bf16_f32 v13, v9, v13
	v_cvt_pk_bf16_f32 v12, v14, v12
	global_store_dwordx2 v[0:1], v[12:13], off offset:32
	v_mul_f32_e32 v9, 0xbfb8aa3b, v85
	v_exp_f32_e32 v12, v9
	v_mul_f32_e32 v9, 0xbfb8aa3b, v84
	v_exp_f32_e32 v14, v9
	v_mul_f32_e32 v9, 0xbfb8aa3b, v83
	v_exp_f32_e32 v13, v9
	v_mul_f32_e32 v9, 0xbfb8aa3b, v82
	v_exp_f32_e32 v15, v9
	s_waitcnt vmcnt(15)
	v_mov_b32_e32 v10, v136
	v_mov_b32_e32 v11, v137
	v_lshlrev_b32_e32 v9, 16, v11
	v_lshlrev_b32_e32 v16, 16, v10
	v_and_b32_e32 v17, 0xffff0000, v11
	v_and_b32_e32 v18, 0xffff0000, v10
	v_pk_add_f32 v[10:11], v[12:13], 1.0 op_sel_hi:[1,0]
	s_nop 0
	v_rcp_f32_e32 v13, v10
	s_nop 0
	v_mul_f32_e32 v12, v16, v13
	v_rcp_f32_e32 v13, v11
	s_nop 0
	v_mul_f32_e32 v9, v9, v13
	v_pk_add_f32 v[10:11], v[14:15], 1.0 op_sel_hi:[1,0]
	s_nop 0
	v_rcp_f32_e32 v14, v10
	s_nop 0
	v_mul_f32_e32 v10, v18, v14
	v_rcp_f32_e32 v14, v11
	s_nop 0
	v_mul_f32_e32 v11, v17, v14
	v_cvt_pk_bf16_f32 v11, v9, v11
	v_cvt_pk_bf16_f32 v10, v12, v10
	v_or_b32_e32 v9, 32, v22
	v_lshrrev_b32_e32 v9, 4, v9
	v_mul_lo_u32 v12, v9, s3
	v_ashrrev_i32_e32 v13, 31, v12
	global_store_dwordx2 v[0:1], v[10:11], off offset:48
	v_lshl_add_u64 v[10:11], v[12:13], 0, v[6:7]
	v_lshlrev_b64 v[10:11], 5, v[10:11]
	v_lshl_add_u64 v[10:11], s[6:7], 0, v[10:11]
	v_lshl_add_u64 v[16:17], v[10:11], 0, v[192:193]
	v_mul_f32_e32 v9, 0xbfb8aa3b, v81
	v_exp_f32_e32 v14, v9
	v_mul_f32_e32 v9, 0xbfb8aa3b, v80
	v_exp_f32_e32 v10, v9
	v_mul_f32_e32 v9, 0xbfb8aa3b, v79
	v_exp_f32_e32 v15, v9
	v_mul_f32_e32 v9, 0xbfb8aa3b, v78
	v_exp_f32_e32 v11, v9
	v_pk_add_f32 v[14:15], v[14:15], 1.0 op_sel_hi:[1,0]
	v_pk_add_f32 v[10:11], v[10:11], 1.0 op_sel_hi:[1,0]
	s_waitcnt vmcnt(15)
	v_mov_b32_e32 v16, v38
	v_mov_b32_e32 v17, v39
	v_lshlrev_b32_e32 v18, 16, v16
	v_rcp_f32_e32 v20, v14
	v_lshlrev_b32_e32 v9, 16, v17
	v_and_b32_e32 v16, 0xffff0000, v16
	v_and_b32_e32 v17, 0xffff0000, v17
	v_mul_f32_e32 v14, v18, v20
	v_rcp_f32_e32 v19, v15
	s_nop 0
	v_mul_f32_e32 v9, v9, v19
	v_rcp_f32_e32 v18, v10
	s_nop 0
	v_mul_f32_e32 v10, v16, v18
	v_rcp_f32_e32 v16, v11
	s_nop 0
	v_mul_f32_e32 v11, v17, v16
	v_cvt_pk_bf16_f32 v11, v9, v11
	v_cvt_pk_bf16_f32 v10, v14, v10
	v_or_b32_e32 v9, 40, v8
	v_lshrrev_b32_e32 v9, 4, v9
	global_store_dwordx2 v[2:3], v[10:11], off offset:64
	v_mul_lo_u32 v10, v9, s3
	v_ashrrev_i32_e32 v11, 31, v10
	v_lshl_add_u64 v[14:15], v[10:11], 0, v[6:7]
	v_lshlrev_b64 v[14:15], 5, v[14:15]
	v_bitop3_b32 v8, v8, 12, 40 bitop3:0xc8
	v_lshl_add_u64 v[14:15], s[6:7], 0, v[14:15]
	v_lshlrev_b32_e32 v8, 1, v8
	v_mov_b32_e32 v9, v193
	v_lshl_add_u64 v[18:19], v[14:15], 0, v[8:9]
	v_mul_f32_e32 v14, 0xbfb8aa3b, v77
	v_mul_f32_e32 v15, 0xbfb8aa3b, v75
	v_exp_f32_e32 v16, v14
	v_exp_f32_e32 v17, v15
	v_mul_f32_e32 v14, 0xbfb8aa3b, v76
	v_mul_f32_e32 v15, 0xbfb8aa3b, v74
	v_exp_f32_e32 v14, v14
	v_pk_add_f32 v[16:17], v[16:17], 1.0 op_sel_hi:[1,0]
	v_exp_f32_e32 v15, v15
	s_waitcnt vmcnt(15)
	v_mov_b32_e32 v18, v124
	v_mov_b32_e32 v19, v125
	v_lshlrev_b32_e32 v21, 16, v18
	v_rcp_f32_e32 v24, v16
	v_lshlrev_b32_e32 v20, 16, v19
	v_and_b32_e32 v18, 0xffff0000, v18
	v_pk_add_f32 v[14:15], v[14:15], 1.0 op_sel_hi:[1,0]
	v_mul_f32_e32 v16, v21, v24
	v_rcp_f32_e32 v23, v17
	v_and_b32_e32 v19, 0xffff0000, v19
	v_mul_f32_e32 v17, v20, v23
	v_rcp_f32_e32 v21, v14
	s_nop 0
	v_mul_f32_e32 v14, v18, v21
	v_rcp_f32_e32 v20, v15
	s_nop 0
	v_mul_f32_e32 v15, v19, v20
	v_cvt_pk_bf16_f32 v15, v17, v15
	v_cvt_pk_bf16_f32 v14, v16, v14
	global_store_dwordx2 v[2:3], v[14:15], off offset:80
	v_or_b32_e32 v14, 48, v22
	v_lshrrev_b32_e32 v14, 4, v14
	v_mul_lo_u32 v14, v14, s3
	v_ashrrev_i32_e32 v15, 31, v14
	v_lshl_add_u64 v[6:7], v[14:15], 0, v[6:7]
	v_lshlrev_b64 v[6:7], 5, v[6:7]
	v_lshl_add_u64 v[6:7], s[6:7], 0, v[6:7]
	v_lshl_add_u64 v[6:7], v[6:7], 0, v[192:193]
	v_mul_f32_e32 v16, 0xbfb8aa3b, v73
	v_mul_f32_e32 v17, 0xbfb8aa3b, v71
	v_exp_f32_e32 v18, v16
	v_exp_f32_e32 v19, v17
	v_mul_f32_e32 v16, 0xbfb8aa3b, v72
	v_mul_f32_e32 v17, 0xbfb8aa3b, v70
	v_exp_f32_e32 v16, v16
	v_pk_add_f32 v[18:19], v[18:19], 1.0 op_sel_hi:[1,0]
	v_exp_f32_e32 v17, v17
	s_waitcnt vmcnt(15)
	v_mov_b32_e32 v20, v140
	v_mov_b32_e32 v21, v141
	v_lshlrev_b32_e32 v23, 16, v20
	v_rcp_f32_e32 v25, v18
	v_lshlrev_b32_e32 v22, 16, v21
	v_and_b32_e32 v20, 0xffff0000, v20
	v_pk_add_f32 v[16:17], v[16:17], 1.0 op_sel_hi:[1,0]
	v_mul_f32_e32 v18, v23, v25
	v_rcp_f32_e32 v24, v19
	v_and_b32_e32 v21, 0xffff0000, v21
	v_mul_f32_e32 v19, v22, v24
	v_rcp_f32_e32 v23, v16
	s_nop 0
	v_mul_f32_e32 v16, v20, v23
	v_rcp_f32_e32 v22, v17
	s_nop 0
	v_mul_f32_e32 v17, v21, v22
	v_cvt_pk_bf16_f32 v17, v19, v17
	v_cvt_pk_bf16_f32 v16, v18, v16
	global_store_dwordx2 v[2:3], v[16:17], off offset:96
	v_mul_f32_e32 v17, 0xbfb8aa3b, v68
	v_mul_f32_e32 v16, 0xbfb8aa3b, v69
	v_exp_f32_e32 v18, v17
	v_mul_f32_e32 v17, 0xbfb8aa3b, v67
	v_exp_f32_e32 v16, v16
	v_exp_f32_e32 v17, v17
	v_mul_f32_e32 v19, 0xbfb8aa3b, v66
	v_exp_f32_e32 v19, v19
	s_waitcnt vmcnt(15)
	v_mov_b32_e32 v6, v144
	v_mov_b32_e32 v7, v145
	v_lshlrev_b32_e32 v20, 16, v7
	v_lshlrev_b32_e32 v21, 16, v6
	v_and_b32_e32 v22, 0xffff0000, v7
	v_and_b32_e32 v23, 0xffff0000, v6
	v_pk_add_f32 v[6:7], v[16:17], 1.0 op_sel_hi:[1,0]
	s_nop 0
	v_rcp_f32_e32 v17, v6
	s_nop 0
	v_mul_f32_e32 v16, v21, v17
	v_rcp_f32_e32 v17, v7
	s_nop 0
	v_mul_f32_e32 v17, v20, v17
	v_pk_add_f32 v[6:7], v[18:19], 1.0 op_sel_hi:[1,0]
	s_nop 0
	v_rcp_f32_e32 v19, v6
	s_nop 0
	v_mul_f32_e32 v6, v23, v19
	v_rcp_f32_e32 v19, v7
	s_nop 0
	v_mul_f32_e32 v7, v22, v19
	v_cvt_pk_bf16_f32 v7, v17, v7
	v_cvt_pk_bf16_f32 v6, v16, v6
	global_store_dwordx2 v[2:3], v[6:7], off offset:112
	v_lshl_add_u64 v[2:3], v[12:13], 0, v[4:5]
	v_lshlrev_b64 v[2:3], 5, v[2:3]
	v_lshl_add_u64 v[2:3], s[6:7], 0, v[2:3]
	v_lshl_add_u64 v[12:13], v[2:3], 0, v[192:193]
	v_mul_f32_e32 v2, 0xbfb8aa3b, v65
	v_mul_f32_e32 v3, 0xbfb8aa3b, v63
	v_exp_f32_e32 v6, v2
	v_exp_f32_e32 v7, v3
	v_mul_f32_e32 v2, 0xbfb8aa3b, v64
	v_mul_f32_e32 v3, 0xbfb8aa3b, v62
	v_exp_f32_e32 v2, v2
	v_pk_add_f32 v[6:7], v[6:7], 1.0 op_sel_hi:[1,0]
	v_exp_f32_e32 v3, v3
	s_waitcnt vmcnt(15)
	v_mov_b32_e32 v12, v26
	v_mov_b32_e32 v13, v27
	v_lshlrev_b32_e32 v17, 16, v12
	v_rcp_f32_e32 v19, v6
	v_lshlrev_b32_e32 v16, 16, v13
	v_and_b32_e32 v12, 0xffff0000, v12
	v_pk_add_f32 v[2:3], v[2:3], 1.0 op_sel_hi:[1,0]
	v_mul_f32_e32 v6, v17, v19
	v_rcp_f32_e32 v18, v7
	v_and_b32_e32 v13, 0xffff0000, v13
	v_mul_f32_e32 v7, v16, v18
	v_rcp_f32_e32 v17, v2
	s_nop 0
	v_mul_f32_e32 v2, v12, v17
	v_rcp_f32_e32 v16, v3
	s_nop 0
	v_mul_f32_e32 v3, v13, v16
	v_cvt_pk_bf16_f32 v3, v7, v3
	v_cvt_pk_bf16_f32 v2, v6, v2
	global_store_dwordx2 v[0:1], v[2:3], off offset:64
	v_lshl_add_u64 v[2:3], v[10:11], 0, v[4:5]
	v_lshlrev_b64 v[2:3], 5, v[2:3]
	v_lshl_add_u64 v[2:3], s[6:7], 0, v[2:3]
	v_lshl_add_u64 v[8:9], v[2:3], 0, v[8:9]
	v_mul_f32_e32 v2, 0xbfb8aa3b, v61
	v_mul_f32_e32 v3, 0xbfb8aa3b, v59
	v_exp_f32_e32 v6, v2
	v_exp_f32_e32 v7, v3
	v_mul_f32_e32 v2, 0xbfb8aa3b, v60
	v_mul_f32_e32 v3, 0xbfb8aa3b, v58
	v_exp_f32_e32 v2, v2
	v_pk_add_f32 v[6:7], v[6:7], 1.0 op_sel_hi:[1,0]
	v_exp_f32_e32 v3, v3
	s_waitcnt vmcnt(15)
	v_mov_b32_e32 v8, v30
	v_mov_b32_e32 v9, v31
	v_lshlrev_b32_e32 v11, 16, v8
	v_rcp_f32_e32 v13, v6
	v_lshlrev_b32_e32 v10, 16, v9
	v_and_b32_e32 v8, 0xffff0000, v8
	v_pk_add_f32 v[2:3], v[2:3], 1.0 op_sel_hi:[1,0]
	v_mul_f32_e32 v6, v11, v13
	v_rcp_f32_e32 v12, v7
	v_and_b32_e32 v9, 0xffff0000, v9
	v_mul_f32_e32 v7, v10, v12
	v_rcp_f32_e32 v11, v2
	s_nop 0
	v_mul_f32_e32 v2, v8, v11
	v_rcp_f32_e32 v10, v3
	s_nop 0
	v_mul_f32_e32 v3, v9, v10
	v_cvt_pk_bf16_f32 v3, v7, v3
	v_cvt_pk_bf16_f32 v2, v6, v2
	global_store_dwordx2 v[0:1], v[2:3], off offset:80
	v_lshl_add_u64 v[2:3], v[14:15], 0, v[4:5]
	v_lshlrev_b64 v[2:3], 5, v[2:3]
	v_lshl_add_u64 v[2:3], s[6:7], 0, v[2:3]
	v_lshl_add_u64 v[2:3], v[2:3], 0, v[192:193]
	v_mul_f32_e32 v4, 0xbfb8aa3b, v57
	v_mul_f32_e32 v5, 0xbfb8aa3b, v55
	v_exp_f32_e32 v6, v4
	v_exp_f32_e32 v7, v5
	v_mul_f32_e32 v4, 0xbfb8aa3b, v56
	v_mul_f32_e32 v5, 0xbfb8aa3b, v54
	v_exp_f32_e32 v4, v4
	v_pk_add_f32 v[6:7], v[6:7], 1.0 op_sel_hi:[1,0]
	v_exp_f32_e32 v5, v5
	s_waitcnt vmcnt(15)
	v_mov_b32_e32 v8, v148
	v_mov_b32_e32 v9, v149
	v_lshlrev_b32_e32 v11, 16, v8
	v_rcp_f32_e32 v13, v6
	v_lshlrev_b32_e32 v10, 16, v9
	v_and_b32_e32 v8, 0xffff0000, v8
	v_pk_add_f32 v[4:5], v[4:5], 1.0 op_sel_hi:[1,0]
	v_mul_f32_e32 v6, v11, v13
	v_rcp_f32_e32 v12, v7
	v_and_b32_e32 v9, 0xffff0000, v9
	v_mul_f32_e32 v7, v10, v12
	v_rcp_f32_e32 v11, v4
	s_nop 0
	v_mul_f32_e32 v4, v8, v11
	v_rcp_f32_e32 v10, v5
	s_nop 0
	v_mul_f32_e32 v5, v9, v10
	v_cvt_pk_bf16_f32 v5, v7, v5
	v_cvt_pk_bf16_f32 v4, v6, v4
	global_store_dwordx2 v[0:1], v[4:5], off offset:96
	v_mul_f32_e32 v5, 0xbfb8aa3b, v52
	v_mul_f32_e32 v4, 0xbfb8aa3b, v53
	v_exp_f32_e32 v6, v5
	v_mul_f32_e32 v5, 0xbfb8aa3b, v51
	v_exp_f32_e32 v4, v4
	v_exp_f32_e32 v5, v5
	v_mul_f32_e32 v7, 0xbfb8aa3b, v50
	v_exp_f32_e32 v7, v7
	s_waitcnt vmcnt(15)
	v_mov_b32_e32 v2, v154
	v_mov_b32_e32 v3, v155
	v_lshlrev_b32_e32 v8, 16, v3
	v_lshlrev_b32_e32 v9, 16, v2
	v_and_b32_e32 v10, 0xffff0000, v3
	v_and_b32_e32 v11, 0xffff0000, v2
	v_pk_add_f32 v[2:3], v[4:5], 1.0 op_sel_hi:[1,0]
	s_nop 0
	v_rcp_f32_e32 v5, v2
	s_nop 0
	v_mul_f32_e32 v4, v9, v5
	v_rcp_f32_e32 v5, v3
	s_nop 0
	v_mul_f32_e32 v5, v8, v5
	v_pk_add_f32 v[2:3], v[6:7], 1.0 op_sel_hi:[1,0]
	s_nop 0
	v_rcp_f32_e32 v7, v2
	s_nop 0
	v_mul_f32_e32 v2, v11, v7
	v_rcp_f32_e32 v7, v3
	s_nop 0
	v_mul_f32_e32 v3, v10, v7
	v_cvt_pk_bf16_f32 v3, v5, v3
	v_cvt_pk_bf16_f32 v2, v4, v2
	global_store_dwordx2 v[0:1], v[2:3], off offset:112
